# attention queue: static XCD-aware first item per workgroup (one MLA pair and one GQA head per XCD share L2), later pops dynamic
# speedup vs baseline: 1.0095x; 1.0095x over previous
.LBB0_312:
	s_mov_b64 s[2:3], exec
	v_readlane_b32 s4, v253, 50
	v_readlane_b32 s5, v253, 51
	v_readlane_b32 s6, v251, 49
	v_readlane_b32 s7, v251, 50
	s_and_b64 s[4:5], s[2:3], s[4:5]
	s_mov_b64 exec, s[4:5]
	s_cbranch_execz .Lpop_noissue
	v_cmp_eq_u32_e32 vcc, -1, v255
	s_cbranch_vccnz .Lpop_static
	v_mov_b32_e32 v255, 1
	s_nop 2
	global_atomic_add v255, v3, v255, s[6:7] sc0
	s_waitcnt vmcnt(0)
	v_add_u32_e32 v255, 0x100, v255
	s_branch .Lpop_noissue
.Lpop_static:
	v_readlane_b32 s6, v253, 4
	s_nop 0
	s_lshr_b32 s6, s6, 3
	s_and_b32 s7, s6, 7
	s_lshr_b32 s6, s6, 3
	s_lshl_b32 s7, s7, 4
	s_and_b32 vcc_lo, s6, 15
	s_add_i32 s7, s7, vcc_lo
	s_lshr_b32 s6, s6, 4
	s_lshl_b32 s6, s6, 7
	s_add_i32 s7, s7, s6
	v_mov_b32_e32 v255, s7
